# final RMSNorm fused into the last layer FFN-down GEMM epilogue (one in-epilogue grid barrier), phase 49 dropped
# baseline (speedup 1.0000x reference)
; #define LAS __attribute__((address_space(3)))
; __device__ __forceinline__ unsigned xb_ld(unsigned* p)              { return __hip_atomic_load(p, __ATOMIC_RELAXED, __HIP_MEMORY_SCOPE_AGENT); }
; __device__ __forceinline__ void xcd_barrier_complete(unsigned* bar, unsigned x, unsigned& nloc, unsigned& nx) {
;     const unsigned G = gridDim.x * gridDim.y * gridDim.z;
;     unsigned sum, cnt, mine, sp = 0u;
;     for (;;) {
;         sum = 0u; cnt = 0u; mine = 0u;
; #pragma unroll
;         for (unsigned j = 0; j < 16; ++j) { const unsigned c = xb_ld(&bar[XB_XCNT(j)]); sum += c; cnt += (c > 0u) ? 1u : 0u; mine = (j == x) ? c : mine; }
; __global__ void __launch_bounds__(NTHREADS, 2) mega(Args a_unused) {
;     ...
;     AP a; a.t = (const LAS unsigned long long*)(lds + ARGS_OFF);
;     XcdBarrier xbar = xcd_barrier_post((unsigned*)(a.ws() + WS_CTL) + 4096, (volatile LAS unsigned*)(lds + 150 * 1024 + 16));
;     const int plo = __builtin_amdgcn_readfirstlane(((const LAS int*)(lds + ARGS_OFF))[70]), phi = __builtin_amdgcn_readfirstlane(((const LAS int*)(lds + ARGS_OFF))[71]);
; #pragma unroll 1
;     for (int p = plo; p < phi; ++p) {
.LBB0_6:
	s_or_b64 exec, exec, s[0:1]
	s_add_i32 s0, 0, 0x25958
	v_mov_b32_e32 v1, s0
	ds_read_b64 v[2:3], v1
	s_mov_b32 s13, 0
	s_waitcnt lgkmcnt(0)
	v_readfirstlane_b32 s0, v2
	v_readfirstlane_b32 s1, v3
	s_add_i32 s1, s1, -1
	s_nop 0
	v_writelane_b32 v253, s0, 4
	s_cmp_ge_i32 s0, s1
	v_writelane_b32 v253, s1, 5
	s_cbranch_scc1 .Lfn_tramp
	v_readlane_b32 s8, v253, 4
	s_add_i32 s0, s8, 1
	v_writelane_b32 v253, s0, 6
	s_add_u32 s0, s4, 0x4200
	s_addc_u32 s1, s3, 0
	v_writelane_b32 v253, s0, 7
	v_lshrrev_b32_e32 v2, 20, v0
	v_lshrrev_b32_e32 v0, 10, v0
	v_writelane_b32 v253, s1, 8
	s_add_u32 s0, s4, 0x4400
	s_addc_u32 s1, s3, 0
	v_writelane_b32 v253, s0, 9
	v_or_b32_e32 v0, v0, v2
	v_mov_b32_e32 v194, 1
	v_writelane_b32 v253, s1, 10
	s_add_u32 s0, s4, 0x4500
	s_addc_u32 s1, s3, 0
	v_writelane_b32 v253, s0, 11
	v_mbcnt_lo_u32_b32 v2, -1, 0
	v_mov_b32_e32 v195, 0x358637bd
	v_writelane_b32 v253, s1, 12
	s_add_u32 s0, s4, 0x4600
	s_addc_u32 s1, s3, 0
	v_writelane_b32 v253, s0, 13
	v_mbcnt_hi_u32_b32 v196, -1, v2
	v_mov_b32_e32 v197, 0xf149f2ca
	v_writelane_b32 v253, s1, 14
	s_add_u32 s0, s4, 0x4700
	s_addc_u32 s1, s3, 0
	v_writelane_b32 v253, s0, 15
	v_mov_b32_e32 v198, 0x80
	v_mov_b32_e32 v199, 0xe00
	v_writelane_b32 v253, s1, 16
	s_add_u32 s0, s4, 0x4800
	s_addc_u32 s1, s3, 0
	v_writelane_b32 v253, s0, 17
	v_mov_b32_e32 v204, 0x461c4000
	v_mov_b32_e32 v205, 0x37000000
	v_writelane_b32 v253, s1, 18
	s_add_u32 s0, s4, 0x4900
	s_addc_u32 s1, s3, 0
	v_writelane_b32 v253, s0, 19
	v_mov_b32_e32 v206, 0x7f800000
	v_not_b32_e32 v207, 63
	v_writelane_b32 v253, s1, 20
	s_add_u32 s0, s4, 0x4a00
	s_addc_u32 s1, s3, 0
	v_writelane_b32 v253, s0, 21
	v_not_b32_e32 v208, 31
	v_mov_b32_e32 v209, 0x7fc00000
	v_writelane_b32 v253, s1, 22
	s_add_u32 s0, s4, 0x4b00
	s_addc_u32 s1, s3, 0
	v_writelane_b32 v253, s0, 23
	s_mov_b32 s81, 0x800000
	s_movk_i32 s36, 0x2c00
	v_writelane_b32 v253, s1, 24
	s_add_u32 s0, s4, 0x4c00
	s_addc_u32 s1, s3, 0
	v_writelane_b32 v253, s0, 25
	s_movk_i32 s37, 0xc00
	s_mov_b32 s82, 0x7f800000
	v_writelane_b32 v253, s1, 26
	s_add_u32 s0, s4, 0x4d00
	s_addc_u32 s1, s3, 0
	v_writelane_b32 v253, s0, 27
	s_movk_i32 s70, 0xc0
	s_movk_i32 s33, 0x1800
	v_writelane_b32 v253, s1, 28
	s_add_u32 s0, s4, 0x4e00
	s_addc_u32 s1, s3, 0
	v_writelane_b32 v253, s0, 29
	s_movk_i32 s84, 0x204
	s_mov_b32 s85, 0x42b17218
	v_writelane_b32 v253, s1, 30
	s_add_u32 s0, s4, 0x4f00
	s_addc_u32 s1, s3, 0
	v_writelane_b32 v253, s0, 31
	s_mov_b64 s[34:35], 0x80
	s_nop 0
	v_writelane_b32 v253, s1, 32
	s_add_u32 s0, s4, 0x5000
	s_addc_u32 s1, s3, 0
	v_writelane_b32 v253, s0, 33
	s_nop 1
	v_writelane_b32 v253, s1, 34
	s_add_u32 s0, s4, 0x5100
	s_addc_u32 s1, s3, 0
	v_writelane_b32 v253, s0, 35
	s_nop 1
	v_writelane_b32 v253, s1, 36
	s_add_u32 s0, s4, 0x5200
	s_addc_u32 s1, s3, 0
	v_writelane_b32 v253, s0, 37
	s_nop 1
	v_writelane_b32 v253, s1, 38
	s_add_u32 s0, s4, 0x5300
	s_addc_u32 s1, s3, 0
	v_writelane_b32 v253, s0, 39
	s_cmp_eq_u32 s7, 15
	s_nop 0
	v_writelane_b32 v253, s1, 40
	s_cselect_b64 s[0:1], -1, 0
	v_writelane_b32 v253, s0, 41
	s_cmp_eq_u32 s7, 14
	s_nop 0
	v_writelane_b32 v253, s1, 42
	s_cselect_b64 s[0:1], -1, 0
	v_writelane_b32 v253, s0, 43
	s_cmp_eq_u32 s7, 13
	s_nop 0
	v_writelane_b32 v253, s1, 44
	s_cselect_b64 s[0:1], -1, 0
	v_writelane_b32 v253, s0, 45
	s_cmp_eq_u32 s7, 12
	s_nop 0
	v_writelane_b32 v253, s1, 46
	s_cselect_b64 s[0:1], -1, 0
	v_writelane_b32 v253, s0, 47
	s_cmp_eq_u32 s7, 11
	s_nop 0
	v_writelane_b32 v253, s1, 48
	s_cselect_b64 s[0:1], -1, 0
	v_writelane_b32 v253, s0, 49
	s_cmp_eq_u32 s7, 10
	s_nop 0
	v_writelane_b32 v253, s1, 50
	s_cselect_b64 s[0:1], -1, 0
	v_writelane_b32 v253, s0, 51
	s_cmp_eq_u32 s7, 9
	s_nop 0
	v_writelane_b32 v253, s1, 52
	s_cselect_b64 s[0:1], -1, 0
	v_writelane_b32 v253, s0, 53
	s_cmp_eq_u32 s7, 8
	s_nop 0
	v_writelane_b32 v253, s1, 54
	s_cselect_b64 s[0:1], -1, 0
	v_writelane_b32 v253, s0, 55
	s_cmp_eq_u32 s7, 7
	s_nop 0
	v_writelane_b32 v253, s1, 56
	s_cselect_b64 s[0:1], -1, 0
	v_writelane_b32 v253, s0, 57
	s_cmp_eq_u32 s7, 6
	s_nop 0
	v_writelane_b32 v253, s1, 58
	s_cselect_b64 s[0:1], -1, 0
	v_writelane_b32 v253, s0, 59
	s_cmp_eq_u32 s7, 5
	s_nop 0
	v_writelane_b32 v253, s1, 60
	s_cselect_b64 s[0:1], -1, 0
	v_writelane_b32 v253, s0, 61
	s_cmp_eq_u32 s7, 4
	s_nop 0
	v_writelane_b32 v253, s1, 62
	s_cselect_b64 s[0:1], -1, 0
	v_writelane_b32 v253, s0, 63
	s_cmp_eq_u32 s7, 3
	s_nop 0
	v_writelane_b32 v254, s1, 0
	s_cselect_b64 s[0:1], -1, 0
	v_writelane_b32 v254, s0, 1
	s_cmp_eq_u32 s7, 2
	s_nop 0
; #define LAS __attribute__((address_space(3)))
; __device__ __forceinline__ int tid_opaque() { int t; asm volatile("v_mov_b32 %0, %1" : "=v"(t) : "v"((int)threadIdx.x)); __builtin_assume(t >= 0 && t < NTHREADS); return t; }
; __device__ __forceinline__ int bid_opaque() { int t; asm volatile("s_mov_b32 %0, %1" : "=s"(t) : "s"((int)blockIdx.x)); __builtin_assume(t >= 0 && t < 1024); return t; }
; __device__ __forceinline__ unsigned xb_ld(unsigned* p)              { return __hip_atomic_load(p, __ATOMIC_RELAXED, __HIP_MEMORY_SCOPE_AGENT); }
; __device__ __forceinline__ void xcd_barrier_complete(unsigned* bar, unsigned x, unsigned& nloc, unsigned& nx) {
;     const unsigned G = gridDim.x * gridDim.y * gridDim.z;
;     unsigned sum, cnt, mine, sp = 0u;
;     for (;;) {
;         sum = 0u; cnt = 0u; mine = 0u;
; #pragma unroll
;         for (unsigned j = 0; j < 16; ++j) { const unsigned c = xb_ld(&bar[XB_XCNT(j)]); sum += c; cnt += (c > 0u) ? 1u : 0u; mine = (j == x) ? c : mine; }
;         if (sum == G) break;
;         __builtin_amdgcn_s_sleep(1);
;         if ((++sp & 255u) == 0u) { if (xb_ld(&bar[XB_TMO])) break; if (sp > XB_SPIN_CAP) { atomicAdd(&bar[XB_TMO], 1u); break; } }
;     }
;     nloc = mine > 0u ? mine : 1u; nx = cnt > 0u ? cnt : 1u;
; __global__ void __launch_bounds__(NTHREADS, 2) mega(Args a_unused) {
;     ...
;     AP a; a.t = (const LAS unsigned long long*)(lds + ARGS_OFF);
;     XcdBarrier xbar = xcd_barrier_post((unsigned*)(a.ws() + WS_CTL) + 4096, (volatile LAS unsigned*)(lds + 150 * 1024 + 16));
;     const int plo = __builtin_amdgcn_readfirstlane(((const LAS int*)(lds + ARGS_OFF))[70]), phi = __builtin_amdgcn_readfirstlane(((const LAS int*)(lds + ARGS_OFF))[71]);
; #pragma unroll 1
;     for (int p = plo; p < phi; ++p) {
;         unsigned char* ws = a.ws();
;         if (p == plo + 1) grid.sync();
;         else if (p > plo) xcd_barrier(xbar);
;         const int tid = tid_opaque(), lane = tid & 63, wave = __builtin_amdgcn_readfirstlane(tid >> 6);
;         const int gw = bid_opaque() * NWAVES + wave, ngw = gridDim.x * NWAVES;
	v_writelane_b32 v254, s1, 2
	s_cselect_b64 s[0:1], -1, 0
	v_writelane_b32 v254, s0, 3
	s_cmp_eq_u32 s7, 1
	s_nop 0
	v_writelane_b32 v254, s1, 4
	s_cselect_b64 s[0:1], -1, 0
	v_writelane_b32 v254, s0, 5
	s_cmp_eq_u32 s7, 0
	s_nop 0
	v_writelane_b32 v254, s1, 6
	s_cselect_b64 s[0:1], -1, 0
	v_writelane_b32 v254, s0, 7
	s_nop 1
	v_writelane_b32 v254, s1, 8
	s_lshl_b32 s0, s7, 8
	s_add_u32 s0, s5, s0
	s_addc_u32 s1, s6, 0
	s_add_u32 s6, s0, 0x1400
	s_addc_u32 s7, s1, 0
	v_writelane_b32 v254, s6, 9
	s_add_u32 s0, s0, 0x2400
	s_addc_u32 s1, s1, 0
	v_writelane_b32 v254, s7, 10
	v_writelane_b32 v254, s0, 11
	s_nop 1
	v_writelane_b32 v254, s1, 12
	s_add_u32 s0, s4, 0x7400
	s_addc_u32 s1, s3, 0
	v_writelane_b32 v254, s0, 13
	s_nop 1
	v_writelane_b32 v254, s1, 14
	s_add_u32 s0, s4, 0x7500
	s_addc_u32 s1, s3, 0
	s_lshl_b32 s72, s10, 3
	s_abs_i32 s74, s72
	v_cvt_f32_u32_e32 v1, s74
	v_writelane_b32 v254, s0, 15
	s_ashr_i32 s73, s72, 31
	s_lshl_b64 s[86:87], s[72:73], 12
	v_rcp_iflag_f32_e32 v1, v1
	v_writelane_b32 v254, s1, 16
	s_mul_i32 s0, s11, s10
	s_mul_i32 s0, s0, s2
	v_mul_f32_e32 v1, 0x4f7ffffe, v1
	v_cvt_u32_f32_e32 v1, v1
	v_writelane_b32 v254, s0, 17
	s_movk_i32 s0, 0x3ff
	v_and_or_b32 v0, v0, s0, v192
	s_sub_i32 s0, 0, s74
	v_readfirstlane_b32 s1, v1
	s_mul_i32 s0, s0, s1
	s_mul_hi_u32 s0, s1, s0
	s_add_i32 s75, s1, s0
	s_mul_i32 s0, s10, 0x7000
	s_mul_hi_i32 s1, s72, 0xe00
	v_writelane_b32 v254, s0, 18
	v_cmp_eq_u32_e64 s[2:3], 0, v0
	s_lshl_b32 s78, s10, 9
	v_writelane_b32 v254, s1, 19
	s_add_i32 s1, 0, 0x25810
	v_writelane_b32 v254, s1, 20
	s_add_i32 s1, 0, 0x25814
	v_writelane_b32 v254, s1, 21
	s_add_i32 s1, 0, 0x25940
	v_writelane_b32 v254, s1, 22
	s_add_i32 s1, 0, 0x25948
	v_writelane_b32 v254, s1, 23
	s_add_i32 s1, 0, 0x25840
	v_writelane_b32 v254, s1, 24
	s_add_i32 s1, 0, 0x25928
	v_writelane_b32 v254, s1, 25
	s_add_i32 s1, 0, 0x25918
	v_writelane_b32 v254, s1, 26
	s_add_i32 s1, 0, 0x25870
	v_writelane_b32 v254, s1, 27
	s_add_i32 s1, 0, 0x258b8
	v_writelane_b32 v254, s1, 28
	s_add_i32 s1, 0, 0x25800
	v_writelane_b32 v254, s1, 29
	s_add_i32 s1, 0, 0x25848
	v_writelane_b32 v254, s1, 30
	s_add_i32 s1, 0, 0x25850
	v_writelane_b32 v254, s1, 31
	s_add_i32 s1, 0, 0x1a700
	v_writelane_b32 v254, s1, 32
	s_add_i32 s1, 0, 0x1a704
	v_writelane_b32 v254, s1, 33
	s_add_i32 s1, 0, 0x1a910
	v_writelane_b32 v254, s1, 34
	s_add_i32 s1, 0, 0x258e8
	v_writelane_b32 v254, s1, 35
	s_add_i32 s1, 0, 0x258f0
	v_writelane_b32 v254, s1, 36
	s_add_i32 s1, 0, 0x25868
	v_writelane_b32 v254, s1, 37
	s_add_i32 s1, 0, 0x258a0
	v_writelane_b32 v254, s1, 38
	s_add_i32 s1, 0, 0x258b0
	v_writelane_b32 v254, s1, 39
	s_add_i32 s1, 0, 0x14800
	v_writelane_b32 v254, s1, 40
	s_add_i32 s1, 0, 0x258c8
	v_writelane_b32 v254, s1, 41
	s_add_i32 s1, 0, 0x258d8
	v_writelane_b32 v254, s1, 42
	s_add_i32 s1, 0, 0x25938
	v_writelane_b32 v254, s1, 43
	s_add_i32 s1, 0, 0x25920
	v_writelane_b32 v254, s1, 44
	s_add_i32 s1, 0, 0x25910
	v_writelane_b32 v254, s1, 45
	s_add_i32 s1, 0, 0x25898
	v_writelane_b32 v254, s1, 46
	s_add_i32 s1, 0, 0x25890
	v_writelane_b32 v254, s1, 47
	s_add_i32 s1, 0, 0x25880
	v_writelane_b32 v254, s1, 48
	s_add_i32 s1, 0, 0x258e0
	v_writelane_b32 v254, s1, 49
	s_add_i32 s1, 0, 0x258d0
	v_writelane_b32 v254, s1, 50
	s_add_i32 s1, 0, 0x25858
	v_writelane_b32 v254, s1, 51
	s_add_i32 s1, 0, 0x25878
	v_writelane_b32 v254, s1, 52
	s_add_i32 s1, 0, 0x25888
	v_writelane_b32 v254, s1, 53
	v_writelane_b32 v254, s2, 54
	s_add_i32 s0, 0, 0x25950
	v_mov_b32_e32 v193, s0
	v_writelane_b32 v254, s3, 55
	s_lshl_b64 s[2:3], s[72:73], 9
	v_writelane_b32 v254, s2, 56
	s_mov_b32 s1, s8
	s_lshl_b32 s80, s10, 10
	v_writelane_b32 v254, s3, 57
	s_lshl_b64 s[2:3], s[72:73], 8
	v_writelane_b32 v254, s2, 58
	s_add_i32 s83, 0, 0x25860
	s_ashr_i32 s79, s78, 31
	v_writelane_b32 v254, s3, 59
	s_lshl_b64 s[2:3], s[72:73], 10
	v_writelane_b32 v254, s2, 60
	s_mov_b32 s73, s0
	s_mov_b32 s0, s72
	v_writelane_b32 v254, s3, 61
	v_writelane_b32 v254, s77, 62
	v_writelane_b32 v254, s0, 63
	s_lshl_b64 s[88:89], s[78:79], 3
	v_mov_b32_e32 v1, 0
	v_writelane_b32 v255, s1, 0
	v_writelane_b32 v255, s74, 1
	v_writelane_b32 v255, s75, 2
	s_mov_b32 s0, s78
	v_writelane_b32 v255, s0, 3
	s_ashr_i32 s9, s10, 31
	s_movk_i32 s11, 0xe00
	v_writelane_b32 v255, s1, 4
	v_writelane_b32 v255, s73, 5
	v_writelane_b32 v255, s80, 6
	v_writelane_b32 v255, s83, 7
	v_writelane_b32 v255, s86, 8
	s_nop 1
	v_writelane_b32 v255, s87, 9
	v_writelane_b32 v255, s88, 10
	s_nop 1
	v_writelane_b32 v255, s89, 11
	s_branch .LBB0_10

;     __device__ __forceinline__ const void* in(int i) const { return (const void*)uni64(t[i]); }
;     __device__ __forceinline__ float* out() const { return (float*)uni64(t[33]); }
;     __device__ __forceinline__ void emit(int row, int pn, int col0, float* v) const {
;     ...
;         case K_WO: case K_DN: {
;             const size_t o = ((size_t)grp * TG + row) * D + col0;
;             const f32x4 a0 = ldg<f32x4>(xi + o), a1 = ldg<f32x4>(xi + o + 4);
;             f32x4 r0, r1; r0.x = a0.x + v[0]; r0.y = a0.y + v[1]; r0.z = a0.z + v[2]; r0.w = a0.w + v[3]; r1.x = a1.x + v[4]; r1.y = a1.y + v[5]; r1.z = a1.z + v[6]; r1.w = a1.w + v[7];
;             stg<f32x4>(xo + o, r0); stg<f32x4>(xo + o + 4, r1);
;         } break;
; __global__ void __launch_bounds__(NTHREADS, 2) mega(Args a_unused) {
;     ...
;         if (p == NPHASE - 1) { rmsnorm_rows_f32(a.out(), (const float*)a.in(I_NFIN), NB * S, gw, ngw, lane); continue; }
.LBB0_462:
	s_cmp_eq_u32 s28, 7
	s_cbranch_scc0 .Lfn_no
	v_readlane_b32 s98, v255, 12
	s_cmpk_gt_u32 s98, 24
	s_cbranch_scc1 .Lfn_epi

;     __device__ __forceinline__ void emit(int row, int pn, int col0, float* v) const {
;     ...
;         case K_WO: case K_DN: {
;             const size_t o = ((size_t)grp * TG + row) * D + col0;
;             const f32x4 a0 = ldg<f32x4>(xi + o), a1 = ldg<f32x4>(xi + o + 4);
;             f32x4 r0, r1; r0.x = a0.x + v[0]; r0.y = a0.y + v[1]; r0.z = a0.z + v[2]; r0.w = a0.w + v[3]; r1.x = a1.x + v[4]; r1.y = a1.y + v[5]; r1.z = a1.z + v[6]; r1.w = a1.w + v[7];
;             stg<f32x4>(xo + o, r0); stg<f32x4>(xo + o + 4, r1);
;         } break;
;     __device__ __forceinline__ void operator()(const f32x4 (&acc)[2][2][4][2], const pg8::Unit& u, int wr, int wc, int fr, int fq) const {
;     ...
;         for (int ai = 0; ai < 2; ++ai)
; #pragma unroll
;             for (int m = 0; m < 4; ++m)
; #pragma unroll
;                 for (int bj = 0; bj < 2; ++bj) {
;                     float v[8]; const f32x4 v0 = acc[ai][bj][m][0], v1 = acc[ai][bj][m][1];
;                     v[0] = v0.x; v[1] = v0.y; v[2] = v0.z; v[3] = v0.w; v[4] = v1.x; v[5] = v1.y; v[6] = v1.z; v[7] = v1.w;
;                     emit(row0 + ai * 128 + m * 16, u.pn, colb + bj * 128, v);
.Lfn_epi:
	v_lshl_add_u32 v202, s43, 8, v186
	s_lshl_b32 s98, s42, 8
	v_or_b32_e32 v203, s98, v188
	v_lshl_add_u32 v242, v202, 10, v203
	v_add_u32_e32 v242, s0, v242
	v_lshlrev_b32_e32 v242, 2, v242
	v_mov_b32_e32 v182, v242
	v_add_u32_e32 v183, 0x10000, v242
	v_add_u32_e32 v184, 0x20000, v242
	v_add_u32_e32 v185, 0x30000, v242
	v_add_u32_e32 v190, 0x80000, v242
	v_add_u32_e32 v191, 0x90000, v242
	v_add_u32_e32 v200, 0xa0000, v242
	v_add_u32_e32 v201, 0xb0000, v242
	global_load_dwordx4 v[210:213], v182, s[74:75]
	global_load_dwordx4 v[214:217], v182, s[74:75] offset:16
	global_load_dwordx4 v[218:221], v182, s[74:75] offset:512
	global_load_dwordx4 v[222:225], v182, s[74:75] offset:528
	global_load_dwordx4 v[226:229], v183, s[74:75]
	global_load_dwordx4 v[230:233], v183, s[74:75] offset:16
	global_load_dwordx4 v[234:237], v183, s[74:75] offset:512
	global_load_dwordx4 v[238:241], v183, s[74:75] offset:528
	global_load_dwordx4 v[132:135], v184, s[74:75]
	global_load_dwordx4 v[136:139], v184, s[74:75] offset:16
	global_load_dwordx4 v[140:143], v184, s[74:75] offset:512
	global_load_dwordx4 v[144:147], v184, s[74:75] offset:528
	global_load_dwordx4 v[148:151], v185, s[74:75]
	global_load_dwordx4 v[152:155], v185, s[74:75] offset:16
	global_load_dwordx4 v[156:159], v185, s[74:75] offset:512
	global_load_dwordx4 v[160:163], v185, s[74:75] offset:528
	s_waitcnt vmcnt(8)
	v_pk_add_f32 v[128:129], v[128:129], v[210:211]
	v_pk_add_f32 v[130:131], v[130:131], v[212:213]
	v_pk_add_f32 v[124:125], v[124:125], v[214:215]
	v_pk_add_f32 v[126:127], v[126:127], v[216:217]
	v_pk_add_f32 v[120:121], v[120:121], v[218:219]
	v_pk_add_f32 v[122:123], v[122:123], v[220:221]
	v_pk_add_f32 v[116:117], v[116:117], v[222:223]
	v_pk_add_f32 v[118:119], v[118:119], v[224:225]
	v_pk_add_f32 v[112:113], v[112:113], v[226:227]
	v_pk_add_f32 v[114:115], v[114:115], v[228:229]
	v_pk_add_f32 v[108:109], v[108:109], v[230:231]
	v_pk_add_f32 v[110:111], v[110:111], v[232:233]
	v_pk_add_f32 v[104:105], v[104:105], v[234:235]
	v_pk_add_f32 v[106:107], v[106:107], v[236:237]
	v_pk_add_f32 v[100:101], v[100:101], v[238:239]
	v_pk_add_f32 v[102:103], v[102:103], v[240:241]
	global_load_dwordx4 v[210:213], v190, s[74:75]
	global_load_dwordx4 v[214:217], v190, s[74:75] offset:16
	global_load_dwordx4 v[218:221], v190, s[74:75] offset:512
	global_load_dwordx4 v[222:225], v190, s[74:75] offset:528
	global_load_dwordx4 v[226:229], v191, s[74:75]
	global_load_dwordx4 v[230:233], v191, s[74:75] offset:16
	global_load_dwordx4 v[234:237], v191, s[74:75] offset:512
	global_load_dwordx4 v[238:241], v191, s[74:75] offset:528
	s_waitcnt vmcnt(8)
	v_pk_add_f32 v[96:97], v[96:97], v[132:133]
	v_pk_add_f32 v[98:99], v[98:99], v[134:135]
	v_pk_add_f32 v[92:93], v[92:93], v[136:137]
	v_pk_add_f32 v[94:95], v[94:95], v[138:139]
	v_pk_add_f32 v[88:89], v[88:89], v[140:141]
	v_pk_add_f32 v[90:91], v[90:91], v[142:143]
	v_pk_add_f32 v[84:85], v[84:85], v[144:145]
	v_pk_add_f32 v[86:87], v[86:87], v[146:147]
	v_pk_add_f32 v[80:81], v[80:81], v[148:149]
	v_pk_add_f32 v[82:83], v[82:83], v[150:151]
	v_pk_add_f32 v[76:77], v[76:77], v[152:153]
	v_pk_add_f32 v[78:79], v[78:79], v[154:155]
	v_pk_add_f32 v[72:73], v[72:73], v[156:157]
	v_pk_add_f32 v[74:75], v[74:75], v[158:159]
	v_pk_add_f32 v[68:69], v[68:69], v[160:161]
	v_pk_add_f32 v[70:71], v[70:71], v[162:163]
	global_load_dwordx4 v[132:135], v200, s[74:75]
	global_load_dwordx4 v[136:139], v200, s[74:75] offset:16
	global_load_dwordx4 v[140:143], v200, s[74:75] offset:512
	global_load_dwordx4 v[144:147], v200, s[74:75] offset:528
	global_load_dwordx4 v[148:151], v201, s[74:75]
	global_load_dwordx4 v[152:155], v201, s[74:75] offset:16
	global_load_dwordx4 v[156:159], v201, s[74:75] offset:512
	global_load_dwordx4 v[160:163], v201, s[74:75] offset:528
	s_waitcnt vmcnt(8)
	v_pk_add_f32 v[64:65], v[64:65], v[210:211]
	v_pk_add_f32 v[66:67], v[66:67], v[212:213]
	v_pk_add_f32 v[60:61], v[60:61], v[214:215]
	v_pk_add_f32 v[62:63], v[62:63], v[216:217]
	v_pk_add_f32 v[56:57], v[56:57], v[218:219]
	v_pk_add_f32 v[58:59], v[58:59], v[220:221]
	v_pk_add_f32 v[52:53], v[52:53], v[222:223]
	v_pk_add_f32 v[54:55], v[54:55], v[224:225]
	v_pk_add_f32 v[48:49], v[48:49], v[226:227]
	v_pk_add_f32 v[50:51], v[50:51], v[228:229]
	v_pk_add_f32 v[44:45], v[44:45], v[230:231]
	v_pk_add_f32 v[46:47], v[46:47], v[232:233]
	v_pk_add_f32 v[40:41], v[40:41], v[234:235]
	v_pk_add_f32 v[42:43], v[42:43], v[236:237]
	v_pk_add_f32 v[36:37], v[36:37], v[238:239]
	v_pk_add_f32 v[38:39], v[38:39], v[240:241]
	s_waitcnt vmcnt(0)
; __device__ __forceinline__ void rmsnorm_rows_f32(float* x, const float* gain, int nrows, int gw, int ngw, int lane) {
;     ...
;         f32x4* xr = (f32x4*)(x + (size_t)r * D) + lane; f32x4 v[4]; float s = 0.f;
; #pragma unroll
;         for (int j = 0; j < 4; ++j) { v[j] = xr[64 * j]; s += (v[j].x * v[j].x + v[j].y * v[j].y) + (v[j].z * v[j].z + v[j].w * v[j].w); }
;         const float rs = rsqrtf(wave_sum(s) * (1.f / D) + 1e-6f);
	v_pk_add_f32 v[32:33], v[32:33], v[132:133]
	v_pk_add_f32 v[34:35], v[34:35], v[134:135]
	v_pk_add_f32 v[28:29], v[28:29], v[136:137]
	v_pk_add_f32 v[30:31], v[30:31], v[138:139]
	v_pk_add_f32 v[24:25], v[24:25], v[140:141]
	v_pk_add_f32 v[26:27], v[26:27], v[142:143]
	v_pk_add_f32 v[20:21], v[20:21], v[144:145]
	v_pk_add_f32 v[22:23], v[22:23], v[146:147]
	v_pk_add_f32 v[16:17], v[16:17], v[148:149]
	v_pk_add_f32 v[18:19], v[18:19], v[150:151]
	v_pk_add_f32 v[12:13], v[12:13], v[152:153]
	v_pk_add_f32 v[14:15], v[14:15], v[154:155]
	v_pk_add_f32 v[8:9], v[8:9], v[156:157]
	v_pk_add_f32 v[10:11], v[10:11], v[158:159]
	v_pk_add_f32 v[4:5], v[4:5], v[160:161]
	v_pk_add_f32 v[6:7], v[6:7], v[162:163]
	v_pk_mul_f32 v[210:211], v[116:117], v[116:117]
	v_pk_fma_f32 v[210:211], v[118:119], v[118:119], v[210:211]
	v_pk_fma_f32 v[210:211], v[120:121], v[120:121], v[210:211]
	v_pk_fma_f32 v[210:211], v[122:123], v[122:123], v[210:211]
	v_pk_fma_f32 v[210:211], v[124:125], v[124:125], v[210:211]
	v_pk_fma_f32 v[210:211], v[126:127], v[126:127], v[210:211]
	v_pk_fma_f32 v[210:211], v[128:129], v[128:129], v[210:211]
	v_pk_fma_f32 v[210:211], v[130:131], v[130:131], v[210:211]
	v_pk_mul_f32 v[212:213], v[100:101], v[100:101]
	v_pk_fma_f32 v[212:213], v[102:103], v[102:103], v[212:213]
	v_pk_fma_f32 v[212:213], v[104:105], v[104:105], v[212:213]
	v_pk_fma_f32 v[212:213], v[106:107], v[106:107], v[212:213]
	v_pk_fma_f32 v[212:213], v[108:109], v[108:109], v[212:213]
	v_pk_fma_f32 v[212:213], v[110:111], v[110:111], v[212:213]
	v_pk_fma_f32 v[212:213], v[112:113], v[112:113], v[212:213]
	v_pk_fma_f32 v[212:213], v[114:115], v[114:115], v[212:213]
	v_pk_mul_f32 v[214:215], v[84:85], v[84:85]
	v_pk_fma_f32 v[214:215], v[86:87], v[86:87], v[214:215]
	v_pk_fma_f32 v[214:215], v[88:89], v[88:89], v[214:215]
	v_pk_fma_f32 v[214:215], v[90:91], v[90:91], v[214:215]
	v_pk_fma_f32 v[214:215], v[92:93], v[92:93], v[214:215]
	v_pk_fma_f32 v[214:215], v[94:95], v[94:95], v[214:215]
	v_pk_fma_f32 v[214:215], v[96:97], v[96:97], v[214:215]
	v_pk_fma_f32 v[214:215], v[98:99], v[98:99], v[214:215]
	v_pk_mul_f32 v[216:217], v[68:69], v[68:69]
	v_pk_fma_f32 v[216:217], v[70:71], v[70:71], v[216:217]
	v_pk_fma_f32 v[216:217], v[72:73], v[72:73], v[216:217]
	v_pk_fma_f32 v[216:217], v[74:75], v[74:75], v[216:217]
	v_pk_fma_f32 v[216:217], v[76:77], v[76:77], v[216:217]
	v_pk_fma_f32 v[216:217], v[78:79], v[78:79], v[216:217]
	v_pk_fma_f32 v[216:217], v[80:81], v[80:81], v[216:217]
	v_pk_fma_f32 v[216:217], v[82:83], v[82:83], v[216:217]
	v_pk_mul_f32 v[218:219], v[52:53], v[52:53]
	v_pk_fma_f32 v[218:219], v[54:55], v[54:55], v[218:219]
	v_pk_fma_f32 v[218:219], v[56:57], v[56:57], v[218:219]
	v_pk_fma_f32 v[218:219], v[58:59], v[58:59], v[218:219]
	v_pk_fma_f32 v[218:219], v[60:61], v[60:61], v[218:219]
	v_pk_fma_f32 v[218:219], v[62:63], v[62:63], v[218:219]
	v_pk_fma_f32 v[218:219], v[64:65], v[64:65], v[218:219]
	v_pk_fma_f32 v[218:219], v[66:67], v[66:67], v[218:219]
	v_pk_mul_f32 v[220:221], v[36:37], v[36:37]
	v_pk_fma_f32 v[220:221], v[38:39], v[38:39], v[220:221]
	v_pk_fma_f32 v[220:221], v[40:41], v[40:41], v[220:221]
	v_pk_fma_f32 v[220:221], v[42:43], v[42:43], v[220:221]
	v_pk_fma_f32 v[220:221], v[44:45], v[44:45], v[220:221]
	v_pk_fma_f32 v[220:221], v[46:47], v[46:47], v[220:221]
	v_pk_fma_f32 v[220:221], v[48:49], v[48:49], v[220:221]
	v_pk_fma_f32 v[220:221], v[50:51], v[50:51], v[220:221]
	v_pk_mul_f32 v[222:223], v[20:21], v[20:21]
	v_pk_fma_f32 v[222:223], v[22:23], v[22:23], v[222:223]
	v_pk_fma_f32 v[222:223], v[24:25], v[24:25], v[222:223]
	v_pk_fma_f32 v[222:223], v[26:27], v[26:27], v[222:223]
	v_pk_fma_f32 v[222:223], v[28:29], v[28:29], v[222:223]
	v_pk_fma_f32 v[222:223], v[30:31], v[30:31], v[222:223]
	v_pk_fma_f32 v[222:223], v[32:33], v[32:33], v[222:223]
	v_pk_fma_f32 v[222:223], v[34:35], v[34:35], v[222:223]
	v_pk_mul_f32 v[224:225], v[4:5], v[4:5]
	v_pk_fma_f32 v[224:225], v[6:7], v[6:7], v[224:225]
	v_pk_fma_f32 v[224:225], v[8:9], v[8:9], v[224:225]
	v_pk_fma_f32 v[224:225], v[10:11], v[10:11], v[224:225]
	v_pk_fma_f32 v[224:225], v[12:13], v[12:13], v[224:225]
	v_pk_fma_f32 v[224:225], v[14:15], v[14:15], v[224:225]
	v_pk_fma_f32 v[224:225], v[16:17], v[16:17], v[224:225]
	v_pk_fma_f32 v[224:225], v[18:19], v[18:19], v[224:225]
	v_add_f32_e32 v210, v210, v211
	v_add_f32_e32 v212, v212, v213
	v_add_f32_e32 v214, v214, v215
	v_add_f32_e32 v216, v216, v217
	v_add_f32_e32 v218, v218, v219
	v_add_f32_e32 v220, v220, v221
	v_add_f32_e32 v222, v222, v223
	v_add_f32_e32 v224, v224, v225
	v_lshrrev_b32_e32 v243, 4, v192
	v_and_b32_e32 v243, 15, v243
	v_lshlrev_b32_e32 v243, 2, v243
	v_lshl_add_u32 v243, v186, 6, v243
	v_add_u32_e32 v243, 0x20000, v243
	ds_write_b32 v243, v210
	ds_write_b32 v243, v212 offset:1024
	ds_write_b32 v243, v214 offset:2048
	ds_write_b32 v243, v216 offset:3072
	ds_write_b32 v243, v218 offset:8192
	ds_write_b32 v243, v220 offset:9216
	ds_write_b32 v243, v222 offset:10240
	ds_write_b32 v243, v224 offset:11264
	v_mov_b32_e32 v132, 0x25950
	ds_read_b64 v[132:133], v132
	s_waitcnt lgkmcnt(0)
	s_barrier
	v_readfirstlane_b32 s98, v132
	v_readfirstlane_b32 s99, v133
	v_readfirstlane_b32 s100, v192
	s_add_u32 s98, s98, 0x40000
	s_addc_u32 s99, s99, 0
	s_cmpk_gt_u32 s100, 0xff
	s_cbranch_scc1 .Lfn_nopart
	v_lshlrev_b32_e32 v0, 6, v192
	v_add_u32_e32 v0, 0x20000, v0
	ds_read_b128 v[226:229], v0
	ds_read_b128 v[230:233], v0 offset:16
	ds_read_b128 v[234:237], v0 offset:32
	ds_read_b128 v[238:241], v0 offset:48
	s_lshl_b32 s100, s42, 14
	s_lshl_b32 s101, s43, 8
	s_add_i32 s100, s100, s101
	v_add_u32_e32 v0, s100, v192
	v_lshlrev_b32_e32 v0, 2, v0
	s_waitcnt lgkmcnt(0)
	v_add_f32_e32 v226, v226, v227
	v_add_f32_e32 v226, v226, v228
	v_add_f32_e32 v226, v226, v229
	v_add_f32_e32 v226, v226, v230
	v_add_f32_e32 v226, v226, v231
	v_add_f32_e32 v226, v226, v232
	v_add_f32_e32 v226, v226, v233
	v_add_f32_e32 v226, v226, v234
	v_add_f32_e32 v226, v226, v235
	v_add_f32_e32 v226, v226, v236
	v_add_f32_e32 v226, v226, v237
	v_add_f32_e32 v226, v226, v238
	v_add_f32_e32 v226, v226, v239
	v_add_f32_e32 v226, v226, v240
	v_add_f32_e32 v226, v226, v241
	global_store_dword v0, v226, s[98:99]
; __device__ __forceinline__ unsigned xb_ld(unsigned* p)              { return __hip_atomic_load(p, __ATOMIC_RELAXED, __HIP_MEMORY_SCOPE_AGENT); }
; __device__ __forceinline__ unsigned xb_add(unsigned* p, unsigned v) { return __hip_atomic_fetch_add(p, v, __ATOMIC_RELAXED, __HIP_MEMORY_SCOPE_AGENT); }
; #define XB_SPIN(cond, bar) do { unsigned _sp = 0; while (cond) { __builtin_amdgcn_s_sleep(1); \
;     if ((++_sp & 255u) == 0u) { if (xb_ld(&(bar)[XB_TMO])) break; if (_sp > XB_SPIN_CAP) { atomicAdd(&(bar)[XB_TMO], 1u); break; } } } } while (0)
; __device__ __forceinline__ void xcd_barrier(const XcdBarrier& b) {
;     asm volatile("s_waitcnt vmcnt(0)" ::: "memory");
;     __syncthreads();
;     if (threadIdx.x == 0) {
;         unsigned* bar = b.bar;
;         __builtin_amdgcn_s_waitcnt(0);
;         unsigned nloc = b.st[0], nx = b.st[1];
;         if (nloc == 0u) { xcd_barrier_complete(bar, b.x, nloc, nx); b.st[0] = nloc; b.st[1] = nx; }
;         const unsigned old = xb_add(&bar[XB_XSUB(b.x)], 1u);
;         const unsigned gen = old / nloc;
;         if (old + 1u == (gen + 1u) * nloc) {
;             __builtin_amdgcn_fence(__ATOMIC_RELEASE, "agent");
;             asm volatile("s_waitcnt vmcnt(0)" ::: "memory");
;             const unsigned og = xb_add(&bar[XB_TOP], 1u);
;             const unsigned tg = og / nx;
;             if (og + 1u == (tg + 1u) * nx) xb_add(&bar[XB_TOPGEN], 1u);
;             else XB_SPIN(xb_ld(&bar[XB_TOPGEN]) == tg, bar);
;             __builtin_amdgcn_fence(__ATOMIC_ACQUIRE, "agent");
;             xb_add(&bar[XB_XGEN(b.x)], 1u);
;             asm volatile("s_waitcnt vmcnt(0)" ::: "memory");
;         } else {
;             XB_SPIN(xb_ld(&bar[XB_XGEN(b.x)]) == gen, bar);
;             __builtin_amdgcn_fence(__ATOMIC_ACQUIRE, "agent");
;             asm volatile("s_waitcnt vmcnt(0)" ::: "memory");
;         }
; __device__ __forceinline__ void rmsnorm_rows_f32(float* x, const float* gain, int nrows, int gw, int ngw, int lane) {
;     ...
;         f32x4* xr = (f32x4*)(x + (size_t)r * D) + lane; f32x4 v[4]; float s = 0.f;
; #pragma unroll
;         for (int j = 0; j < 4; ++j) { v[j] = xr[64 * j]; s += (v[j].x * v[j].x + v[j].y * v[j].y) + (v[j].z * v[j].z + v[j].w * v[j].w); }
;         const float rs = rsqrtf(wave_sum(s) * (1.f / D) + 1e-6f);
; #pragma unroll
;         for (int j = 0; j < 4; ++j) xr[64 * j] = v[j] * rs * gv[j];
.Lfn_nopart:
	s_waitcnt vmcnt(0)
	s_barrier
	v_readfirstlane_b32 s100, v192
	s_cmp_lg_u32 s100, 0
	s_cbranch_scc1 .Lfn_bw
	buffer_wbl2 sc1
	s_waitcnt vmcnt(0)
	v_readlane_b32 s100, v255, 12
	s_lshr_b32 s100, s100, 2
	s_add_i32 s100, s100, 16
	s_lshl_b32 s100, s100, 2
	v_mov_b32_e32 v0, s100
	v_lshl_add_u64 v[134:135], v[132:133], 0, v[0:1]
	s_mov_b64 exec, 1
	flat_atomic_add v[134:135], v194
	s_mov_b64 exec, -1
	s_mov_b32 s101, 0
.Lfn_spin:
	flat_load_dword v0, v[134:135] sc1
	s_waitcnt vmcnt(0) lgkmcnt(0)
	v_readfirstlane_b32 s100, v0
	s_cmpk_gt_u32 s100, 0xff
	s_cbranch_scc1 .Lfn_rel
	s_sleep 2
	s_add_i32 s101, s101, 1
	s_cmpk_lt_u32 s101, 0x800
	s_cbranch_scc1 .Lfn_spin
.Lfn_rel:
	buffer_inv sc1
	s_waitcnt vmcnt(0)
.Lfn_bw:
	s_barrier
	v_lshlrev_b32_e32 v136, 2, v202
	v_add_u32_e32 v137, 0x10000, v136
	v_add_u32_e32 v138, 0x20000, v136
	v_add_u32_e32 v139, 0x30000, v136
	global_load_dword v210, v136, s[98:99]
	global_load_dword v211, v137, s[98:99]
	global_load_dword v212, v138, s[98:99]
	global_load_dword v213, v139, s[98:99]
	global_load_dword v214, v136, s[98:99] offset:64
	global_load_dword v215, v137, s[98:99] offset:64
	global_load_dword v216, v138, s[98:99] offset:64
	global_load_dword v217, v139, s[98:99] offset:64
	global_load_dword v218, v136, s[98:99] offset:128
	global_load_dword v219, v137, s[98:99] offset:128
	global_load_dword v220, v138, s[98:99] offset:128
	global_load_dword v221, v139, s[98:99] offset:128
	global_load_dword v222, v136, s[98:99] offset:192
	global_load_dword v223, v137, s[98:99] offset:192
	global_load_dword v224, v138, s[98:99] offset:192
	global_load_dword v225, v139, s[98:99] offset:192
	global_load_dword v226, v136, s[98:99] offset:512
	global_load_dword v227, v137, s[98:99] offset:512
	global_load_dword v228, v138, s[98:99] offset:512
	global_load_dword v229, v139, s[98:99] offset:512
	global_load_dword v230, v136, s[98:99] offset:576
	global_load_dword v231, v137, s[98:99] offset:576
	global_load_dword v232, v138, s[98:99] offset:576
	global_load_dword v233, v139, s[98:99] offset:576
	global_load_dword v234, v136, s[98:99] offset:640
	global_load_dword v235, v137, s[98:99] offset:640
	global_load_dword v236, v138, s[98:99] offset:640
	global_load_dword v237, v139, s[98:99] offset:640
	global_load_dword v238, v136, s[98:99] offset:704
	global_load_dword v239, v137, s[98:99] offset:704
	global_load_dword v240, v138, s[98:99] offset:704
	global_load_dword v241, v139, s[98:99] offset:704
	v_mov_b32_e32 v0, 0x25940
	ds_read_b64 v[140:141], v0
	v_lshlrev_b32_e32 v0, 2, v203
	v_mov_b32_e32 v142, 0x358637bd
	s_waitcnt lgkmcnt(0)
	v_readfirstlane_b32 s100, v140
	v_readfirstlane_b32 s101, v141
	s_nop 4
	global_load_dwordx4 v[144:147], v0, s[100:101]
	global_load_dwordx4 v[148:151], v0, s[100:101] offset:16
	global_load_dwordx4 v[152:155], v0, s[100:101] offset:512
	global_load_dwordx4 v[156:159], v0, s[100:101] offset:528
	s_waitcnt vmcnt(0)
	v_add_f32_e32 v210, v210, v211
	v_add_f32_e32 v210, v210, v212
	v_add_f32_e32 v210, v210, v213
	v_fmamk_f32 v210, v210, 0x3a800000, v142
	v_add_f32_e32 v214, v214, v215
	v_add_f32_e32 v214, v214, v216
	v_add_f32_e32 v214, v214, v217
	v_fmamk_f32 v214, v214, 0x3a800000, v142
	v_add_f32_e32 v218, v218, v219
	v_add_f32_e32 v218, v218, v220
	v_add_f32_e32 v218, v218, v221
	v_fmamk_f32 v218, v218, 0x3a800000, v142
	v_add_f32_e32 v222, v222, v223
	v_add_f32_e32 v222, v222, v224
	v_add_f32_e32 v222, v222, v225
	v_fmamk_f32 v222, v222, 0x3a800000, v142
	v_add_f32_e32 v226, v226, v227
	v_add_f32_e32 v226, v226, v228
	v_add_f32_e32 v226, v226, v229
	v_fmamk_f32 v226, v226, 0x3a800000, v142
	v_add_f32_e32 v230, v230, v231
	v_add_f32_e32 v230, v230, v232
	v_add_f32_e32 v230, v230, v233
	v_fmamk_f32 v230, v230, 0x3a800000, v142
	v_add_f32_e32 v234, v234, v235
	v_add_f32_e32 v234, v234, v236
	v_add_f32_e32 v234, v234, v237
	v_fmamk_f32 v234, v234, 0x3a800000, v142
	v_add_f32_e32 v238, v238, v239
	v_add_f32_e32 v238, v238, v240
	v_add_f32_e32 v238, v238, v241
	v_fmamk_f32 v238, v238, 0x3a800000, v142
	v_rsq_f32_e32 v210, v210
	v_rsq_f32_e32 v214, v214
	v_rsq_f32_e32 v218, v218
	v_rsq_f32_e32 v222, v222
	v_rsq_f32_e32 v226, v226
	v_rsq_f32_e32 v230, v230
	v_rsq_f32_e32 v234, v234
	v_rsq_f32_e32 v238, v238
	s_nop 0
	v_pk_mul_f32 v[128:129], v[128:129], v[210:211] op_sel_hi:[1,0]
	v_pk_mul_f32 v[130:131], v[130:131], v[210:211] op_sel_hi:[1,0]
	v_pk_mul_f32 v[124:125], v[124:125], v[210:211] op_sel_hi:[1,0]
	v_pk_mul_f32 v[126:127], v[126:127], v[210:211] op_sel_hi:[1,0]
	v_pk_mul_f32 v[128:129], v[144:145], v[128:129]
	v_pk_mul_f32 v[130:131], v[146:147], v[130:131]
	v_pk_mul_f32 v[124:125], v[148:149], v[124:125]
	v_pk_mul_f32 v[126:127], v[150:151], v[126:127]
	global_store_dwordx4 v182, v[128:131], s[66:67]
	global_store_dwordx4 v182, v[124:127], s[66:67] offset:16
	v_pk_mul_f32 v[120:121], v[120:121], v[210:211] op_sel_hi:[1,0]
	v_pk_mul_f32 v[122:123], v[122:123], v[210:211] op_sel_hi:[1,0]
	v_pk_mul_f32 v[116:117], v[116:117], v[210:211] op_sel_hi:[1,0]
	v_pk_mul_f32 v[118:119], v[118:119], v[210:211] op_sel_hi:[1,0]
	v_pk_mul_f32 v[120:121], v[152:153], v[120:121]
	v_pk_mul_f32 v[122:123], v[154:155], v[122:123]
	v_pk_mul_f32 v[116:117], v[156:157], v[116:117]
	v_pk_mul_f32 v[118:119], v[158:159], v[118:119]
	global_store_dwordx4 v182, v[120:123], s[66:67] offset:512
	global_store_dwordx4 v182, v[116:119], s[66:67] offset:528
	v_pk_mul_f32 v[112:113], v[112:113], v[214:215] op_sel_hi:[1,0]
	v_pk_mul_f32 v[114:115], v[114:115], v[214:215] op_sel_hi:[1,0]
	v_pk_mul_f32 v[108:109], v[108:109], v[214:215] op_sel_hi:[1,0]
	v_pk_mul_f32 v[110:111], v[110:111], v[214:215] op_sel_hi:[1,0]
; __device__ __forceinline__ void rmsnorm_rows_f32(float* x, const float* gain, int nrows, int gw, int ngw, int lane) {
;     ...
; #pragma unroll
;         for (int j = 0; j < 4; ++j) xr[64 * j] = v[j] * rs * gv[j];
	v_pk_mul_f32 v[112:113], v[144:145], v[112:113]
	v_pk_mul_f32 v[114:115], v[146:147], v[114:115]
	v_pk_mul_f32 v[108:109], v[148:149], v[108:109]
	v_pk_mul_f32 v[110:111], v[150:151], v[110:111]
	global_store_dwordx4 v183, v[112:115], s[66:67]
	global_store_dwordx4 v183, v[108:111], s[66:67] offset:16
	v_pk_mul_f32 v[104:105], v[104:105], v[214:215] op_sel_hi:[1,0]
	v_pk_mul_f32 v[106:107], v[106:107], v[214:215] op_sel_hi:[1,0]
	v_pk_mul_f32 v[100:101], v[100:101], v[214:215] op_sel_hi:[1,0]
	v_pk_mul_f32 v[102:103], v[102:103], v[214:215] op_sel_hi:[1,0]
	v_pk_mul_f32 v[104:105], v[152:153], v[104:105]
	v_pk_mul_f32 v[106:107], v[154:155], v[106:107]
	v_pk_mul_f32 v[100:101], v[156:157], v[100:101]
	v_pk_mul_f32 v[102:103], v[158:159], v[102:103]
	global_store_dwordx4 v183, v[104:107], s[66:67] offset:512
	global_store_dwordx4 v183, v[100:103], s[66:67] offset:528
	v_pk_mul_f32 v[96:97], v[96:97], v[218:219] op_sel_hi:[1,0]
	v_pk_mul_f32 v[98:99], v[98:99], v[218:219] op_sel_hi:[1,0]
	v_pk_mul_f32 v[92:93], v[92:93], v[218:219] op_sel_hi:[1,0]
	v_pk_mul_f32 v[94:95], v[94:95], v[218:219] op_sel_hi:[1,0]
	v_pk_mul_f32 v[96:97], v[144:145], v[96:97]
	v_pk_mul_f32 v[98:99], v[146:147], v[98:99]
	v_pk_mul_f32 v[92:93], v[148:149], v[92:93]
	v_pk_mul_f32 v[94:95], v[150:151], v[94:95]
	global_store_dwordx4 v184, v[96:99], s[66:67]
	global_store_dwordx4 v184, v[92:95], s[66:67] offset:16
	v_pk_mul_f32 v[88:89], v[88:89], v[218:219] op_sel_hi:[1,0]
	v_pk_mul_f32 v[90:91], v[90:91], v[218:219] op_sel_hi:[1,0]
	v_pk_mul_f32 v[84:85], v[84:85], v[218:219] op_sel_hi:[1,0]
	v_pk_mul_f32 v[86:87], v[86:87], v[218:219] op_sel_hi:[1,0]
	v_pk_mul_f32 v[88:89], v[152:153], v[88:89]
	v_pk_mul_f32 v[90:91], v[154:155], v[90:91]
	v_pk_mul_f32 v[84:85], v[156:157], v[84:85]
	v_pk_mul_f32 v[86:87], v[158:159], v[86:87]
	global_store_dwordx4 v184, v[88:91], s[66:67] offset:512
	global_store_dwordx4 v184, v[84:87], s[66:67] offset:528
	v_pk_mul_f32 v[80:81], v[80:81], v[222:223] op_sel_hi:[1,0]
	v_pk_mul_f32 v[82:83], v[82:83], v[222:223] op_sel_hi:[1,0]
	v_pk_mul_f32 v[76:77], v[76:77], v[222:223] op_sel_hi:[1,0]
	v_pk_mul_f32 v[78:79], v[78:79], v[222:223] op_sel_hi:[1,0]
	v_pk_mul_f32 v[80:81], v[144:145], v[80:81]
	v_pk_mul_f32 v[82:83], v[146:147], v[82:83]
	v_pk_mul_f32 v[76:77], v[148:149], v[76:77]
	v_pk_mul_f32 v[78:79], v[150:151], v[78:79]
	global_store_dwordx4 v185, v[80:83], s[66:67]
	global_store_dwordx4 v185, v[76:79], s[66:67] offset:16
	v_pk_mul_f32 v[72:73], v[72:73], v[222:223] op_sel_hi:[1,0]
	v_pk_mul_f32 v[74:75], v[74:75], v[222:223] op_sel_hi:[1,0]
	v_pk_mul_f32 v[68:69], v[68:69], v[222:223] op_sel_hi:[1,0]
	v_pk_mul_f32 v[70:71], v[70:71], v[222:223] op_sel_hi:[1,0]
	v_pk_mul_f32 v[72:73], v[152:153], v[72:73]
	v_pk_mul_f32 v[74:75], v[154:155], v[74:75]
	v_pk_mul_f32 v[68:69], v[156:157], v[68:69]
	v_pk_mul_f32 v[70:71], v[158:159], v[70:71]
	global_store_dwordx4 v185, v[72:75], s[66:67] offset:512
	global_store_dwordx4 v185, v[68:71], s[66:67] offset:528
	v_pk_mul_f32 v[64:65], v[64:65], v[226:227] op_sel_hi:[1,0]
	v_pk_mul_f32 v[66:67], v[66:67], v[226:227] op_sel_hi:[1,0]
	v_pk_mul_f32 v[60:61], v[60:61], v[226:227] op_sel_hi:[1,0]
	v_pk_mul_f32 v[62:63], v[62:63], v[226:227] op_sel_hi:[1,0]
	v_pk_mul_f32 v[64:65], v[144:145], v[64:65]
	v_pk_mul_f32 v[66:67], v[146:147], v[66:67]
	v_pk_mul_f32 v[60:61], v[148:149], v[60:61]
	v_pk_mul_f32 v[62:63], v[150:151], v[62:63]
	global_store_dwordx4 v190, v[64:67], s[66:67]
	global_store_dwordx4 v190, v[60:63], s[66:67] offset:16
	v_pk_mul_f32 v[56:57], v[56:57], v[226:227] op_sel_hi:[1,0]
	v_pk_mul_f32 v[58:59], v[58:59], v[226:227] op_sel_hi:[1,0]
; __device__ __forceinline__ void rmsnorm_rows_f32(float* x, const float* gain, int nrows, int gw, int ngw, int lane) {
;     ...
; #pragma unroll
;         for (int j = 0; j < 4; ++j) xr[64 * j] = v[j] * rs * gv[j];
	v_pk_mul_f32 v[52:53], v[52:53], v[226:227] op_sel_hi:[1,0]
	v_pk_mul_f32 v[54:55], v[54:55], v[226:227] op_sel_hi:[1,0]
	v_pk_mul_f32 v[56:57], v[152:153], v[56:57]
	v_pk_mul_f32 v[58:59], v[154:155], v[58:59]
	v_pk_mul_f32 v[52:53], v[156:157], v[52:53]
	v_pk_mul_f32 v[54:55], v[158:159], v[54:55]
	global_store_dwordx4 v190, v[56:59], s[66:67] offset:512
	global_store_dwordx4 v190, v[52:55], s[66:67] offset:528
	v_pk_mul_f32 v[48:49], v[48:49], v[230:231] op_sel_hi:[1,0]
	v_pk_mul_f32 v[50:51], v[50:51], v[230:231] op_sel_hi:[1,0]
	v_pk_mul_f32 v[44:45], v[44:45], v[230:231] op_sel_hi:[1,0]
	v_pk_mul_f32 v[46:47], v[46:47], v[230:231] op_sel_hi:[1,0]
	v_pk_mul_f32 v[48:49], v[144:145], v[48:49]
	v_pk_mul_f32 v[50:51], v[146:147], v[50:51]
	v_pk_mul_f32 v[44:45], v[148:149], v[44:45]
	v_pk_mul_f32 v[46:47], v[150:151], v[46:47]
	global_store_dwordx4 v191, v[48:51], s[66:67]
	global_store_dwordx4 v191, v[44:47], s[66:67] offset:16
	v_pk_mul_f32 v[40:41], v[40:41], v[230:231] op_sel_hi:[1,0]
	v_pk_mul_f32 v[42:43], v[42:43], v[230:231] op_sel_hi:[1,0]
	v_pk_mul_f32 v[36:37], v[36:37], v[230:231] op_sel_hi:[1,0]
	v_pk_mul_f32 v[38:39], v[38:39], v[230:231] op_sel_hi:[1,0]
	v_pk_mul_f32 v[40:41], v[152:153], v[40:41]
	v_pk_mul_f32 v[42:43], v[154:155], v[42:43]
	v_pk_mul_f32 v[36:37], v[156:157], v[36:37]
	v_pk_mul_f32 v[38:39], v[158:159], v[38:39]
	global_store_dwordx4 v191, v[40:43], s[66:67] offset:512
	global_store_dwordx4 v191, v[36:39], s[66:67] offset:528
	v_pk_mul_f32 v[32:33], v[32:33], v[234:235] op_sel_hi:[1,0]
	v_pk_mul_f32 v[34:35], v[34:35], v[234:235] op_sel_hi:[1,0]
	v_pk_mul_f32 v[28:29], v[28:29], v[234:235] op_sel_hi:[1,0]
	v_pk_mul_f32 v[30:31], v[30:31], v[234:235] op_sel_hi:[1,0]
	v_pk_mul_f32 v[32:33], v[144:145], v[32:33]
	v_pk_mul_f32 v[34:35], v[146:147], v[34:35]
	v_pk_mul_f32 v[28:29], v[148:149], v[28:29]
	v_pk_mul_f32 v[30:31], v[150:151], v[30:31]
	global_store_dwordx4 v200, v[32:35], s[66:67]
	global_store_dwordx4 v200, v[28:31], s[66:67] offset:16
	v_pk_mul_f32 v[24:25], v[24:25], v[234:235] op_sel_hi:[1,0]
	v_pk_mul_f32 v[26:27], v[26:27], v[234:235] op_sel_hi:[1,0]
	v_pk_mul_f32 v[20:21], v[20:21], v[234:235] op_sel_hi:[1,0]
	v_pk_mul_f32 v[22:23], v[22:23], v[234:235] op_sel_hi:[1,0]
	v_pk_mul_f32 v[24:25], v[152:153], v[24:25]
	v_pk_mul_f32 v[26:27], v[154:155], v[26:27]
	v_pk_mul_f32 v[20:21], v[156:157], v[20:21]
	v_pk_mul_f32 v[22:23], v[158:159], v[22:23]
	global_store_dwordx4 v200, v[24:27], s[66:67] offset:512
	global_store_dwordx4 v200, v[20:23], s[66:67] offset:528
	v_pk_mul_f32 v[16:17], v[16:17], v[238:239] op_sel_hi:[1,0]
	v_pk_mul_f32 v[18:19], v[18:19], v[238:239] op_sel_hi:[1,0]
	v_pk_mul_f32 v[12:13], v[12:13], v[238:239] op_sel_hi:[1,0]
	v_pk_mul_f32 v[14:15], v[14:15], v[238:239] op_sel_hi:[1,0]
	v_pk_mul_f32 v[16:17], v[144:145], v[16:17]
	v_pk_mul_f32 v[18:19], v[146:147], v[18:19]
	v_pk_mul_f32 v[12:13], v[148:149], v[12:13]
	v_pk_mul_f32 v[14:15], v[150:151], v[14:15]
	global_store_dwordx4 v201, v[16:19], s[66:67]
	global_store_dwordx4 v201, v[12:15], s[66:67] offset:16
	v_pk_mul_f32 v[8:9], v[8:9], v[238:239] op_sel_hi:[1,0]
	v_pk_mul_f32 v[10:11], v[10:11], v[238:239] op_sel_hi:[1,0]
	v_pk_mul_f32 v[4:5], v[4:5], v[238:239] op_sel_hi:[1,0]
	v_pk_mul_f32 v[6:7], v[6:7], v[238:239] op_sel_hi:[1,0]
	v_pk_mul_f32 v[8:9], v[152:153], v[8:9]
	v_pk_mul_f32 v[10:11], v[154:155], v[10:11]
	v_pk_mul_f32 v[4:5], v[156:157], v[4:5]
	v_pk_mul_f32 v[6:7], v[158:159], v[6:7]
	global_store_dwordx4 v201, v[8:11], s[66:67] offset:512
	global_store_dwordx4 v201, v[4:7], s[66:67] offset:528
	s_branch .LBB0_1375
.Lfn_tramp:
	s_branch .LBB0_1525
